# NSA items: one static s_setprio 1 for waves 4-7 for the item duration (strategy 4), on top of v10
# speedup vs baseline: 1.0039x; 1.0039x over previous
; #define LAS __attribute__((address_space(3)))
; __device__ __forceinline__ void nsa_item(const Params& p, int l, int item, lptr lds) {
;     int tid_ = threadIdx.x; asm volatile("" : "+v"(tid_)); const int tid = tid_, wave = __builtin_amdgcn_readfirstlane(tid >> 6), lane = tid & 63, fr = lane & 15, fq = lane >> 4;
;     const int qt = item & 31, g = (item >> 5) & 1, b = item >> 6; const int t0 = qt * 64, cur = qt;
;     const bf16_t* projb = (const bf16_t*)(p.ws + WS_PROJ) + (size_t)b * SEQ * PLD; bf16_t* ys = (bf16_t*)(p.ws + WS_YS);
;     const bf16_t* kcmp = (const bf16_t*)(p.ws + WS_KCMP) + (size_t)(b * 2 + g) * 8192; const bf16_t* vcmpT = (const bf16_t*)(p.ws + WS_VCMPT) + (size_t)(b * 2 + g) * 8192;
;     lptr Ks = lds, VT = lds + 9216, Ks1 = lds + 125184, VT1 = lds + 134400; LAS float* Pc = (LAS float*)(lds + 18432); LAS unsigned* selm = (LAS unsigned*)(lds + 52224); lptr Kc = lds + 52480, VcT = lds + 70912;
;     const int r = wave >> 1, qh = wave & 1, hh = g * 4 + r; const float slope = exp2f(-(float)(hh + 1)) * 1.4426950408889634f;
;     int trow[2]; lptr Qs = lds + 88320; const int qrow = wave * 32;
; #pragma unroll
;     for (int mi = 0; mi < 2; ++mi) { trow[mi] = t0 + qh * 32 + mi * 16 + fr;
; #pragma unroll
;         for (int ks = 0; ks < 2; ++ks) *(LAS bf16x8*)(Qs + ((size_t)(qrow + mi * 16 + fr) * 72 + ks * 32 + fq * 8) * 2) = *(const bf16x8*)(projb + (size_t)trow[mi] * PLD + C_Q + hh * 64 + ks * 32 + fq * 8);
;     }
;     ...
;     f32x4 outa[2][4];
; #pragma unroll
;     for (int k = 0; k < 2; ++k) { const int idx = tid + k * 512;
;         { const int row = idx >> 3, ch = idx & 7; *(LAS u32x4*)(Kc + ((size_t)row * 72 + ch * 8) * 2) = *(const u32x4*)(kcmp + row * 64 + ch * 8); }
;         { const int row = idx >> 4, ch = idx & 15; *(LAS u32x4*)(VcT + ((size_t)row * 136 + ch * 8) * 2) = *(const u32x4*)(vcmpT + row * 128 + ch * 8); } }
;     __syncthreads();
.LBB0_1887:
	s_and_b64 vcc, exec, s[2:3]
	s_cbranch_vccz .LBB0_1934
	s_add_i32 s30, s88, 0xffffff80
	s_lshr_b32 s93, s30, 4
	v_mov_b32_e32 v77, v216
	s_bfe_u32 s28, s88, 0x30001
	s_sub_i32 s40, 31, s93
	s_lshl_b32 s2, s28, 11
	v_readfirstlane_b32 s34, v77
	s_ashr_i32 s38, s34, 6
	s_cmp_lt_u32 s38, 4
	s_cbranch_scc1 .Lmy_nsa_p0
	s_setprio 1
.Lmy_nsa_p0:
	s_and_b32 s31, s88, 1
	s_lshl_b32 s24, s40, 6
	v_writelane_b32 v254, s2, 60
	s_mul_i32 s2, s28, 0x1320000
	s_add_u32 s42, s68, s2
	s_addc_u32 s43, s69, 0
	s_ashr_i32 s37, s34, 7
	s_lshl_b32 s2, s31, 2
	s_add_i32 s36, s37, s2
	s_add_i32 s2, s36, 1
	v_cvt_f32_i32_e32 v75, s2
	s_mov_b32 s2, 0x42fc0000
	s_and_b32 s92, s38, 1
	v_and_b32_e32 v119, 15, v77
	v_cmp_lt_f32_e32 vcc, s2, v75
	s_and_b64 s[2:3], vcc, exec
	s_cselect_b32 s2, 0xffffffc0, 0
	s_lshl_b32 s39, s92, 5
	s_or_b32 s3, s39, s24
	v_mov_b32_e32 v0, 0x42800000
	v_or_b32_e32 v139, s3, v119
	s_lshl_b32 s24, s36, 6
	v_cndmask_b32_e32 v76, 0, v0, vcc
	s_ashr_i32 s25, s24, 31
	v_mul_u32_u24_e32 v106, 0x2640, v139
	v_mov_b32_e32 v107, v1
	v_mov_b32_e32 v0, 0x26400
	v_lshl_add_u64 v[2:3], s[42:43], 0, v[106:107]
	s_lshl_b64 s[24:25], s[24:25], 1
	v_mad_u32_u24 v0, v139, s70, v0
	v_lshl_add_u64 v[10:11], v[2:3], 0, s[24:25]
	v_lshl_add_u64 v[2:3], s[42:43], 0, v[0:1]
	v_writelane_b32 v254, s24, 61
	s_lshl_b32 s3, s31, 14
	v_ashrrev_i32_e32 v166, 3, v77
	v_writelane_b32 v254, s25, 62
	v_lshl_add_u64 v[18:19], v[2:3], 0, s[24:25]
	s_lshl_b32 s24, s28, 15
	s_or_b32 s3, s24, s3
	v_readlane_b32 s24, v253, 13
	s_add_u32 s24, s24, s3
	v_readlane_b32 s25, v253, 14
	v_lshlrev_b32_e32 v2, 3, v77
	s_addc_u32 s25, s25, 0
	v_readlane_b32 s28, v253, 11
	v_and_b32_e32 v74, 56, v2
	v_readlane_b32 s29, v253, 12
	s_add_u32 s28, s28, s3
	v_lshlrev_b32_e32 v0, 1, v74
	v_and_b32_e32 v34, 0x78, v2
	s_addc_u32 s29, s29, 0
	v_lshl_add_u64 v[12:13], s[24:25], 0, v[0:1]
	v_lshlrev_b32_e32 v0, 1, v34
	v_lshl_add_u64 v[26:27], s[28:29], 0, v[0:1]
	v_add_u32_e32 v0, 0x200, v77
	v_ashrrev_i32_e32 v38, 3, v0
	v_ashrrev_i32_e32 v35, 4, v77
	v_lshlrev_b32_e32 v14, 6, v38
	v_ashrrev_i32_e32 v39, 4, v0
	v_and_b32_e32 v0, 48, v77
	v_lshlrev_b32_e32 v2, 6, v166
	v_lshlrev_b32_e32 v4, 7, v35
	v_ashrrev_i32_e32 v15, 31, v14
	v_lshl_add_u64 v[10:11], v[10:11], 0, v[0:1]
	s_mov_b64 s[24:25], 0x1400
	s_movk_i32 s3, 0x1000
	v_ashrrev_i32_e32 v3, 31, v2
	v_ashrrev_i32_e32 v5, 31, v4
	v_lshl_add_u64 v[28:29], v[14:15], 1, v[12:13]
	v_lshl_add_u64 v[14:15], v[10:11], 0, s[24:25]
	v_add_co_u32_e32 v10, vcc, s3, v10
	v_lshl_add_u64 v[2:3], v[2:3], 1, v[12:13]
	v_lshl_add_u64 v[6:7], v[4:5], 1, v[26:27]
	v_lshlrev_b32_e32 v30, 7, v39
	v_addc_co_u32_e32 v11, vcc, 0, v11, vcc
	v_lshl_add_u64 v[18:19], v[18:19], 0, v[0:1]
	global_load_dwordx4 v[2:5], v[2:3], off
	s_nop 0
	global_load_dwordx4 v[6:9], v[6:7], off
	s_nop 0
	global_load_dwordx4 v[10:13], v[10:11], off offset:1024
	s_nop 0
	global_load_dwordx4 v[14:17], v[14:15], off offset:64
	v_lshl_add_u64 v[22:23], v[18:19], 0, s[24:25]
	v_add_co_u32_e32 v18, vcc, s3, v18
	v_ashrrev_i32_e32 v31, 31, v30
	s_nop 0
	v_addc_co_u32_e32 v19, vcc, 0, v19, vcc
	v_lshl_add_u64 v[30:31], v[30:31], 1, v[26:27]
	global_load_dwordx4 v[18:21], v[18:19], off offset:1024
	s_nop 0
	global_load_dwordx4 v[22:25], v[22:23], off offset:64
	s_nop 0
	global_load_dwordx4 v[26:29], v[28:29], off
	s_nop 0
	global_load_dwordx4 v[30:33], v[30:31], off
	v_lshl_or_b32 v36, s38, 5, v119
	s_movk_i32 s28, 0x48
	v_bfe_u32 v81, v77, 4, 2
	v_mul_lo_u32 v40, v36, s28
	v_mul_lo_u32 v36, v166, s28
	s_movk_i32 s3, 0x88
	v_lshlrev_b32_e32 v79, 3, v81
	v_add_lshl_u32 v167, v36, v74, 1
	v_mad_u64_u32 v[36:37], s[24:25], v35, s3, v[34:35]
	v_mad_u64_u32 v[34:35], s[24:25], v39, s3, v[34:35]
	v_add_lshl_u32 v123, v40, v79, 1
	v_readlane_b32 s3, v253, 42
	v_add_u32_e32 v41, 0x480, v40
	v_readlane_b32 s29, v253, 41
	v_add_u32_e32 v35, s3, v123
	v_mul_u32_u24_e32 v78, 0x48, v119
	s_waitcnt vmcnt(5)
	ds_write_b128 v35, v[10:13]
	s_waitcnt vmcnt(4)
	ds_write_b128 v35, v[14:17] offset:64
	v_add_u32_e32 v10, v41, v79
	v_lshl_add_u32 v42, v36, 1, s29
	v_mad_u64_u32 v[36:37], s[24:25], v38, s28, v[74:75]
	v_lshl_add_u32 v10, v10, 1, s3
	v_add_lshl_u32 v168, v79, v78, 1
	v_add_u32_e32 v122, 0, v167
	v_lshl_add_u32 v36, v36, 1, 0
	v_lshl_add_u32 v34, v34, 1, s29
	s_waitcnt vmcnt(3)
	ds_write_b128 v10, v[18:21]
	s_waitcnt vmcnt(2)
	ds_write_b128 v10, v[22:25] offset:64
	ds_write_b128 v122, v[2:5] offset:52480
	ds_write_b128 v42, v[6:9]
	s_waitcnt vmcnt(1)
	ds_write_b128 v36, v[26:29] offset:52480
	s_waitcnt vmcnt(0)
	ds_write_b128 v34, v[30:33]
	v_add_u32_e32 v2, 0, v168
	s_waitcnt lgkmcnt(0)
	s_barrier
; __device__ __forceinline__ f32x4 MF(bf16x8 a, bf16x8 b, f32x4 c) { return __builtin_amdgcn_mfma_f32_16x16x32_bf16(a, b, c, 0, 0, 0); }
; __device__ __forceinline__ void nsa_item(const Params& p, int l, int item, lptr lds) {
;     ...
; #pragma unroll
;         for (int ks = 0; ks < 2; ++ks)
; #pragma unroll
;             for (int ni = 0; ni < 8; ++ni) { const bf16x8 kf = ldfrag(Kc, (ni * 16 + fr) * 72 + ks * 32 + fq * 8);
; #pragma unroll
;                 for (int mi = 0; mi < 2; ++mi) S[mi][ni] = MF(kf, ldfrag(Qs, (qrow + mi * 16 + fr) * 72 + ks * 32 + fq * 8), S[mi][ni]); }
	ds_read_b128 v[2:5], v2 offset:52480
	v_mov_b32_e32 v6, 0x480
	v_mad_u32_u24 v38, v119, s28, v6
	ds_read_b128 v[6:9], v35
	ds_read_b128 v[10:13], v10
	v_mad_u32_u24 v39, v119, s28, v239
	v_add_lshl_u32 v169, v79, v38, 1
	s_waitcnt lgkmcnt(1)
	v_mfma_f32_16x16x32_bf16 v[18:21], v[2:5], v[6:9], 0
	v_add_u32_e32 v14, 0, v169
	ds_read_b128 v[14:17], v14 offset:52480
	v_mov_b32_e32 v26, 0xd80
	s_waitcnt lgkmcnt(1)
	v_mfma_f32_16x16x32_bf16 v[22:25], v[2:5], v[10:13], 0
	v_add_u32_e32 v2, v79, v39
	v_lshl_add_u32 v2, v2, 1, 0
	ds_read_b128 v[2:5], v2 offset:52480
	v_mad_u32_u24 v82, v119, s28, v26
	v_add_u32_e32 v26, v79, v82
	v_lshl_add_u32 v26, v26, 1, 0
	ds_read_b128 v[26:29], v26 offset:52480
	s_waitcnt lgkmcnt(1)
	v_mfma_f32_16x16x32_bf16 v[34:37], v[2:5], v[6:9], 0
	v_mov_b32_e32 v50, 0x1680
	v_mad_u32_u24 v104, v119, s28, v50
	v_mov_b32_e32 v66, 0x1f80
	v_mfma_f32_16x16x32_bf16 v[42:45], v[2:5], v[10:13], 0
	v_mov_b32_e32 v2, 0x1200
	v_mad_u32_u24 v83, v119, s28, v2
	v_add_u32_e32 v2, v79, v83
	v_lshl_add_u32 v2, v2, 1, 0
	ds_read_b128 v[2:5], v2 offset:52480
	s_waitcnt lgkmcnt(1)
	v_mfma_f32_16x16x32_bf16 v[46:49], v[26:29], v[6:9], 0
	v_mad_u32_u24 v107, v119, s28, v66
	v_or_b32_e32 v80, 32, v79
	v_add_lshl_u32 v170, v80, v78, 1
	v_mfma_f32_16x16x32_bf16 v[50:53], v[26:29], v[10:13], 0
	v_add_u32_e32 v26, v79, v104
	v_lshl_add_u32 v26, v26, 1, 0
	ds_read_b128 v[26:29], v26 offset:52480
	s_waitcnt lgkmcnt(1)
	v_mfma_f32_16x16x32_bf16 v[54:57], v[2:5], v[6:9], 0
	v_add_lshl_u32 v171, v80, v38, 1
	v_lshlrev_b32_e32 v138, 2, v81
	v_or_b32_e32 v141, 16, v139
	v_mfma_f32_16x16x32_bf16 v[58:61], v[2:5], v[10:13], 0
	v_mov_b32_e32 v2, 0x1b00
	v_mad_u32_u24 v105, v119, s28, v2
	v_add_u32_e32 v2, v79, v105
	v_lshl_add_u32 v2, v2, 1, 0
	ds_read_b128 v[2:5], v2 offset:52480
	s_waitcnt lgkmcnt(1)
	v_mfma_f32_16x16x32_bf16 v[62:65], v[26:29], v[6:9], 0
	s_mov_b32 s24, 0x41780000
	v_add_u32_e32 v0, 0, v0
	s_cmpk_gt_u32 s34, 0x7f
	v_mfma_f32_16x16x32_bf16 v[66:69], v[26:29], v[10:13], 0
	v_add_u32_e32 v26, v79, v107
	v_lshl_add_u32 v26, v26, 1, 0
	ds_read_b128 v[26:29], v26 offset:52480
	s_waitcnt lgkmcnt(1)
	v_mfma_f32_16x16x32_bf16 v[70:73], v[2:5], v[6:9], 0
	s_mov_b32 s38, 0
	v_writelane_b32 v254, s39, 63
	v_mfma_f32_16x16x32_bf16 v[84:87], v[2:5], v[10:13], 0
	v_add_u32_e32 v2, 0, v170
	v_mfma_f32_16x16x32_bf16 v[30:33], v[14:17], v[6:9], 0
	s_waitcnt lgkmcnt(0)
	v_mfma_f32_16x16x32_bf16 v[88:91], v[26:29], v[6:9], 0
	ds_read_b128 v[6:9], v2 offset:52480
	v_add_u32_e32 v2, v40, v80
	v_lshl_add_u32 v2, v2, 1, s3
	ds_read_b128 v[96:99], v2
	v_mfma_f32_16x16x32_bf16 v[14:17], v[14:17], v[10:13], 0
	v_mfma_f32_16x16x32_bf16 v[92:95], v[26:29], v[10:13], 0
	v_add_u32_e32 v10, v41, v80
	v_lshl_add_u32 v10, v10, 1, s3
	v_add_u32_e32 v11, 0, v171
	s_waitcnt lgkmcnt(0)
	v_mfma_f32_16x16x32_bf16 v[2:5], v[6:9], v[96:99], v[18:21]
	ds_read_b128 v[100:103], v10
	ds_read_b128 v[10:13], v11 offset:52480
	s_nop 0
	v_add_u32_e32 v18, v80, v39
	v_lshl_add_u32 v18, v18, 1, 0
	ds_read_b128 v[18:21], v18 offset:52480
	s_waitcnt lgkmcnt(2)
	v_mfma_f32_16x16x32_bf16 v[26:29], v[6:9], v[100:103], v[22:25]
	s_waitcnt lgkmcnt(1)
	v_mfma_f32_16x16x32_bf16 v[6:9], v[10:13], v[96:99], v[30:33]
	v_mfma_f32_16x16x32_bf16 v[38:41], v[10:13], v[100:103], v[14:17]
	v_add_u32_e32 v10, v80, v82
	v_lshl_add_u32 v10, v10, 1, 0
	ds_read_b128 v[22:25], v10 offset:52480
	s_waitcnt lgkmcnt(1)
	v_mfma_f32_16x16x32_bf16 v[10:13], v[18:21], v[96:99], v[34:37]
	v_mfma_f32_16x16x32_bf16 v[42:45], v[18:21], v[100:103], v[42:45]
	v_add_u32_e32 v18, v80, v83
	v_lshl_add_u32 v18, v18, 1, 0
	ds_read_b128 v[30:33], v18 offset:52480
	v_sub_f32_e32 v18, v76, v75
	v_exp_f32_e32 v75, v18
	s_waitcnt lgkmcnt(1)
	v_mfma_f32_16x16x32_bf16 v[14:17], v[22:25], v[96:99], v[46:49]
	v_add_u32_e32 v18, v80, v104
	v_lshl_add_u32 v18, v18, 1, 0
	ds_read_b128 v[34:37], v18 offset:52480
	v_mfma_f32_16x16x32_bf16 v[46:49], v[22:25], v[100:103], v[50:53]
	v_ldexp_f32 v22, v75, s2
	v_mul_f32_e32 v140, 0x3fb8aa3b, v22
	v_add_u32_e32 v22, v80, v105
	v_lshl_add_u32 v22, v22, 1, 0
	s_waitcnt lgkmcnt(1)
	v_mfma_f32_16x16x32_bf16 v[108:111], v[30:33], v[100:103], v[58:61]
	ds_read_b128 v[50:53], v22 offset:52480
	v_or_b32_e32 v75, 3, v138
	v_or_b32_e32 v76, 2, v138
	v_mfma_f32_16x16x32_bf16 v[18:21], v[30:33], v[96:99], v[54:57]
	v_and_b32_e32 v30, 64, v234
	v_add_u32_e32 v82, 64, v30
	v_add_u32_e32 v30, v80, v107
	v_lshl_add_u32 v30, v30, 1, 0
	ds_read_b128 v[54:57], v30 offset:52480
	v_xor_b32_e32 v58, 16, v234
	v_cmp_lt_i32_e32 vcc, v58, v82
	s_waitcnt lgkmcnt(2)
	v_mfma_f32_16x16x32_bf16 v[22:25], v[34:37], v[96:99], v[62:65]
	s_mov_b32 s2, 0xf149f2ca
	v_mfma_f32_16x16x32_bf16 v[64:67], v[34:37], v[100:103], v[66:69]
	v_cndmask_b32_e32 v34, v234, v58, vcc
	v_lshlrev_b32_e32 v172, 2, v34
	v_xor_b32_e32 v34, 32, v234
	v_cmp_lt_i32_e32 vcc, v34, v82
	s_waitcnt lgkmcnt(1)
	v_mfma_f32_16x16x32_bf16 v[30:33], v[50:53], v[96:99], v[70:73]
	v_mfma_f32_16x16x32_bf16 v[60:63], v[50:53], v[100:103], v[84:87]
	v_cndmask_b32_e32 v50, v234, v34, vcc
	v_cvt_f32_u32_e32 v52, v141
	v_lshlrev_b32_e32 v173, 2, v50
	s_waitcnt lgkmcnt(0)
; __device__ __forceinline__ void nsa_item(const Params& p, int l, int item, lptr lds) {
;     ...
;         for (int mi = 0; mi < 2; ++mi) { const int t = trow[mi]; float mx = -1e30f;
; #pragma unroll
;             for (int ni = 0; ni < 8; ++ni)
; #pragma unroll
;                 for (int jj = 0; jj < 4; ++jj) { const int ci = ni * 16 + fq * 4 + jj; const bool valid = (16 * ci + 31 <= t);
;                     const float s = valid ? S[mi][ni][jj] - slope * ((float)t - (16.f * (float)ci + 15.5f)) : -1e30f; S[mi][ni][jj] = s; mx = fmaxf(mx, s); }
	v_mfma_f32_16x16x32_bf16 v[34:37], v[54:57], v[96:99], v[88:91]
	v_or_b32_e32 v84, 0x70, v138
	v_lshlrev_b32_e32 v51, 4, v84
	v_or_b32_e32 v121, 31, v51
	v_mfma_f32_16x16x32_bf16 v[56:59], v[54:57], v[100:103], v[92:95]
	v_lshlrev_b32_e32 v103, 6, v81
	v_or_b32_e32 v53, 0x710, v103
	v_cvt_f32_u32_e32 v55, v53
	v_cvt_f32_u32_e32 v54, v51
	v_or_b32_e32 v51, 0x730, v103
	v_or_b32_e32 v120, 0x72f, v103
	v_cmp_le_u32_e32 vcc, v120, v141
	v_pk_add_f32 v[54:55], v[54:55], s[24:25] op_sel_hi:[1,0]
	v_or_b32_e32 v85, 0x60, v138
	v_pk_add_f32 v[68:69], v[52:53], v[54:55] op_sel_hi:[0,1] neg_lo:[0,1] neg_hi:[0,1]
	v_or_b32_e32 v53, 0x720, v103
	v_pk_fma_f32 v[56:57], v[140:141], v[68:69], v[56:57] op_sel_hi:[0,1,1] neg_lo:[1,0,0] neg_hi:[1,0,0]
	v_cvt_f32_u32_e32 v69, v51
	v_cvt_f32_u32_e32 v68, v53
	v_cndmask_b32_e32 v70, v244, v57, vcc
	v_cmp_le_u32_e32 vcc, v121, v141
	v_lshlrev_b32_e32 v51, 4, v85
	v_add_u32_e32 v125, 0x74f, v103
	v_cndmask_b32_e32 v72, v244, v56, vcc
	v_pk_add_f32 v[56:57], v[68:69], s[24:25] op_sel_hi:[1,0]
	v_or_b32_e32 v124, 0x73f, v103
	v_pk_add_f32 v[68:69], v[52:53], v[56:57] op_sel_hi:[0,1] neg_lo:[0,1] neg_hi:[0,1]
	v_or_b32_e32 v53, 0x610, v103
	v_pk_fma_f32 v[58:59], v[140:141], v[68:69], v[58:59] op_sel_hi:[0,1,1] neg_lo:[1,0,0] neg_hi:[1,0,0]
	v_cvt_f32_u32_e32 v69, v53
	v_cvt_f32_u32_e32 v68, v51
	v_cmp_le_u32_e32 vcc, v125, v141
	v_or_b32_e32 v127, 31, v51
	v_or_b32_e32 v51, 0x630, v103
	v_cndmask_b32_e32 v71, v244, v59, vcc
	v_cmp_le_u32_e32 vcc, v124, v141
	v_or_b32_e32 v126, 0x62f, v103
	v_or_b32_e32 v87, 0x50, v138
	v_cndmask_b32_e32 v73, v244, v58, vcc
	v_pk_add_f32 v[58:59], v[68:69], s[24:25] op_sel_hi:[1,0]
	v_cmp_le_u32_e32 vcc, v126, v141
	v_pk_add_f32 v[68:69], v[52:53], v[58:59] op_sel_hi:[0,1] neg_lo:[0,1] neg_hi:[0,1]
	v_or_b32_e32 v53, 0x620, v103
	v_pk_fma_f32 v[60:61], v[140:141], v[68:69], v[60:61] op_sel_hi:[0,1,1] neg_lo:[1,0,0] neg_hi:[1,0,0]
	v_cvt_f32_u32_e32 v69, v51
	v_cvt_f32_u32_e32 v68, v53
	v_cndmask_b32_e32 v83, v244, v61, vcc
	v_cmp_le_u32_e32 vcc, v127, v141
	v_lshlrev_b32_e32 v51, 4, v87
	v_add_u32_e32 v129, 0x64f, v103
	v_cndmask_b32_e32 v91, v244, v60, vcc
	v_pk_add_f32 v[60:61], v[68:69], s[24:25] op_sel_hi:[1,0]
	v_or_b32_e32 v128, 0x63f, v103
	v_pk_add_f32 v[68:69], v[52:53], v[60:61] op_sel_hi:[0,1] neg_lo:[0,1] neg_hi:[0,1]
	v_or_b32_e32 v53, 0x510, v103
	v_pk_fma_f32 v[62:63], v[140:141], v[68:69], v[62:63] op_sel_hi:[0,1,1] neg_lo:[1,0,0] neg_hi:[1,0,0]
	v_cvt_f32_u32_e32 v69, v53
	v_cvt_f32_u32_e32 v68, v51
	v_cmp_le_u32_e32 vcc, v129, v141
	v_or_b32_e32 v131, 31, v51
	v_or_b32_e32 v51, 0x530, v103
	v_cndmask_b32_e32 v92, v244, v63, vcc
	v_cmp_le_u32_e32 vcc, v128, v141
	v_or_b32_e32 v130, 0x52f, v103
	v_or_b32_e32 v86, 64, v138
	v_cndmask_b32_e32 v93, v244, v62, vcc
	v_pk_add_f32 v[62:63], v[68:69], s[24:25] op_sel_hi:[1,0]
	v_cmp_le_u32_e32 vcc, v130, v141
	v_pk_add_f32 v[68:69], v[52:53], v[62:63] op_sel_hi:[0,1] neg_lo:[0,1] neg_hi:[0,1]
	v_or_b32_e32 v53, 0x520, v103
	v_pk_fma_f32 v[64:65], v[140:141], v[68:69], v[64:65] op_sel_hi:[0,1,1] neg_lo:[1,0,0] neg_hi:[1,0,0]
	v_cvt_f32_u32_e32 v69, v51
	v_cvt_f32_u32_e32 v68, v53
	v_cndmask_b32_e32 v94, v244, v65, vcc
	v_cmp_le_u32_e32 vcc, v131, v141
	v_lshlrev_b32_e32 v51, 4, v86
	v_add_u32_e32 v133, 0x54f, v103
	v_cndmask_b32_e32 v95, v244, v64, vcc
	v_pk_add_f32 v[64:65], v[68:69], s[24:25] op_sel_hi:[1,0]
	v_or_b32_e32 v132, 0x53f, v103
	v_pk_add_f32 v[68:69], v[52:53], v[64:65] op_sel_hi:[0,1] neg_lo:[0,1] neg_hi:[0,1]
	v_or_b32_e32 v53, 0x410, v103
	v_pk_fma_f32 v[66:67], v[140:141], v[68:69], v[66:67] op_sel_hi:[0,1,1] neg_lo:[1,0,0] neg_hi:[1,0,0]
	v_cvt_f32_u32_e32 v69, v53
	v_cvt_f32_u32_e32 v68, v51
	v_cmp_le_u32_e32 vcc, v133, v141
	v_or_b32_e32 v134, 0x42f, v103
	v_or_b32_e32 v135, 31, v51
	v_cndmask_b32_e32 v96, v244, v67, vcc
	v_cmp_le_u32_e32 vcc, v132, v141
	v_add_u32_e32 v137, 0x44f, v103
	v_or_b32_e32 v89, 48, v138
	v_cndmask_b32_e32 v97, v244, v66, vcc
	v_pk_add_f32 v[66:67], v[68:69], s[24:25] op_sel_hi:[1,0]
	v_cmp_le_u32_e32 vcc, v134, v141
	v_pk_add_f32 v[68:69], v[52:53], v[66:67] op_sel_hi:[0,1] neg_lo:[0,1] neg_hi:[0,1]
	v_pk_fma_f32 v[68:69], v[140:141], v[68:69], v[108:109] op_sel_hi:[0,1,1] neg_lo:[1,0,0] neg_hi:[1,0,0]
	v_cndmask_b32_e32 v51, v244, v69, vcc
	v_or_b32_e32 v53, 0x430, v103
	v_or_b32_e32 v69, 0x420, v103
	v_cvt_f32_u32_e32 v99, v53
	v_cvt_f32_u32_e32 v98, v69
	v_cmp_le_u32_e32 vcc, v135, v141
	v_or_b32_e32 v136, 0x43f, v103
	v_or_b32_e32 v142, 0x32f, v103
	v_cndmask_b32_e32 v53, v244, v68, vcc
	v_pk_add_f32 v[68:69], v[98:99], s[24:25] op_sel_hi:[1,0]
	v_cmp_le_u32_e32 vcc, v137, v141
	v_pk_add_f32 v[98:99], v[52:53], v[68:69] op_sel_hi:[0,1] neg_lo:[0,1] neg_hi:[0,1]
	v_pk_fma_f32 v[100:101], v[140:141], v[98:99], v[110:111] op_sel_hi:[0,1,1] neg_lo:[1,0,0] neg_hi:[1,0,0]
	v_cndmask_b32_e32 v98, v244, v101, vcc
	v_lshlrev_b32_e32 v101, 4, v89
	v_or_b32_e32 v99, 0x310, v103
	v_cvt_f32_u32_e32 v105, v99
	v_cvt_f32_u32_e32 v104, v101
	v_cmp_le_u32_e32 vcc, v136, v141
	v_or_b32_e32 v143, 31, v101
	v_or_b32_e32 v88, 32, v138
	v_pk_add_f32 v[104:105], v[104:105], s[24:25] op_sel_hi:[1,0]
	v_cndmask_b32_e32 v99, v244, v100, vcc
	v_pk_add_f32 v[100:101], v[52:53], v[104:105] op_sel_hi:[0,1] neg_lo:[0,1] neg_hi:[0,1]
	v_pk_fma_f32 v[100:101], v[140:141], v[100:101], v[46:47] op_sel_hi:[0,1,1] neg_lo:[1,0,0] neg_hi:[1,0,0]
	v_cmp_le_u32_e32 vcc, v142, v141
	v_or_b32_e32 v47, 0x330, v103
	v_cvt_f32_u32_e32 v109, v47
	v_cndmask_b32_e32 v46, v244, v101, vcc
	v_or_b32_e32 v101, 0x320, v103
	v_cvt_f32_u32_e32 v108, v101
	v_lshlrev_b32_e32 v47, 4, v88
	v_cvt_f32_u32_e32 v112, v47
; __device__ __forceinline__ void nsa_item(const Params& p, int l, int item, lptr lds) {
;     ...
;         for (int mi = 0; mi < 2; ++mi) { const int t = trow[mi]; float mx = -1e30f;
; #pragma unroll
;             for (int ni = 0; ni < 8; ++ni)
; #pragma unroll
;                 for (int jj = 0; jj < 4; ++jj) { const int ci = ni * 16 + fq * 4 + jj; const bool valid = (16 * ci + 31 <= t);
;                     const float s = valid ? S[mi][ni][jj] - slope * ((float)t - (16.f * (float)ci + 15.5f)) : -1e30f; S[mi][ni][jj] = s; mx = fmaxf(mx, s); }
;             mx = fmaxf(mx, __shfl_xor(mx, 16)); mx = fmaxf(mx, __shfl_xor(mx, 32)); float sum = 0.f;
	v_cmp_le_u32_e32 vcc, v143, v141
	v_pk_add_f32 v[108:109], v[108:109], s[24:25] op_sel_hi:[1,0]
	v_add_u32_e32 v145, 0x34f, v103
	v_pk_add_f32 v[110:111], v[52:53], v[108:109] op_sel_hi:[0,1] neg_lo:[0,1] neg_hi:[0,1]
	v_pk_fma_f32 v[110:111], v[140:141], v[110:111], v[48:49] op_sel_hi:[0,1,1] neg_lo:[1,0,0] neg_hi:[1,0,0]
	v_or_b32_e32 v49, 0x210, v103
	v_cvt_f32_u32_e32 v113, v49
	v_cndmask_b32_e32 v100, v244, v100, vcc
	v_or_b32_e32 v144, 0x33f, v103
	v_cmp_le_u32_e32 vcc, v145, v141
	v_or_b32_e32 v147, 31, v47
	v_or_b32_e32 v47, 0x220, v103
	v_cndmask_b32_e32 v48, v244, v111, vcc
	v_cmp_le_u32_e32 vcc, v144, v141
	v_cvt_f32_u32_e32 v114, v47
	v_or_b32_e32 v146, 0x22f, v103
	v_cndmask_b32_e32 v101, v244, v110, vcc
	v_pk_add_f32 v[110:111], v[112:113], s[24:25] op_sel_hi:[1,0]
	v_cmp_le_u32_e32 vcc, v146, v141
	v_pk_add_f32 v[112:113], v[52:53], v[110:111] op_sel_hi:[0,1] neg_lo:[0,1] neg_hi:[0,1]
	v_pk_fma_f32 v[112:113], v[140:141], v[112:113], v[42:43] op_sel_hi:[0,1,1] neg_lo:[1,0,0] neg_hi:[1,0,0]
	v_or_b32_e32 v43, 0x230, v103
	v_cvt_f32_u32_e32 v115, v43
	v_cndmask_b32_e32 v42, v244, v113, vcc
	v_cmp_le_u32_e32 vcc, v147, v141
	v_or_b32_e32 v90, 16, v138
	v_or_b32_e32 v49, 0x110, v103
	v_cndmask_b32_e32 v47, v244, v112, vcc
	v_pk_add_f32 v[112:113], v[114:115], s[24:25] op_sel_hi:[1,0]
	v_cvt_f32_u32_e32 v117, v49
	v_pk_add_f32 v[114:115], v[52:53], v[112:113] op_sel_hi:[0,1] neg_lo:[0,1] neg_hi:[0,1]
	v_pk_fma_f32 v[114:115], v[140:141], v[114:115], v[44:45] op_sel_hi:[0,1,1] neg_lo:[1,0,0] neg_hi:[1,0,0]
	v_lshlrev_b32_e32 v45, 4, v90
	v_cvt_f32_u32_e32 v116, v45
	v_add_u32_e32 v148, 0x24f, v103
	v_or_b32_e32 v43, 0x23f, v103
	v_cmp_le_u32_e32 vcc, v148, v141
	v_or_b32_e32 v149, 0x12f, v103
	v_or_b32_e32 v45, 31, v45
	v_cndmask_b32_e32 v44, v244, v115, vcc
	v_cmp_le_u32_e32 vcc, v43, v141
	v_add_u32_e32 v153, 0x14f, v103
	v_or_b32_e32 v81, 1, v138
	v_cndmask_b32_e32 v49, v244, v114, vcc
	v_pk_add_f32 v[114:115], v[116:117], s[24:25] op_sel_hi:[1,0]
	v_cmp_le_u32_e32 vcc, v149, v141
	v_pk_add_f32 v[116:117], v[52:53], v[114:115] op_sel_hi:[0,1] neg_lo:[0,1] neg_hi:[0,1]
	v_pk_fma_f32 v[38:39], v[140:141], v[116:117], v[38:39] op_sel_hi:[0,1,1] neg_lo:[1,0,0] neg_hi:[1,0,0]
	v_cndmask_b32_e32 v150, v244, v39, vcc
	v_or_b32_e32 v39, 0x130, v103
	v_or_b32_e32 v116, 0x120, v103
	v_cvt_f32_u32_e32 v117, v39
	v_cvt_f32_u32_e32 v116, v116
	v_cmp_le_u32_e32 vcc, v45, v141
	v_or_b32_e32 v152, 0x13f, v103
	v_lshlrev_b32_e32 v107, 4, v81
	v_cndmask_b32_e32 v151, v244, v38, vcc
	v_pk_add_f32 v[38:39], v[116:117], s[24:25] op_sel_hi:[1,0]
	v_cmp_le_u32_e32 vcc, v153, v141
	v_pk_add_f32 v[116:117], v[52:53], v[38:39] op_sel_hi:[0,1] neg_lo:[0,1] neg_hi:[0,1]
	v_pk_fma_f32 v[40:41], v[140:141], v[116:117], v[40:41] op_sel_hi:[0,1,1] neg_lo:[1,0,0] neg_hi:[1,0,0]
	v_cndmask_b32_e32 v154, v244, v41, vcc
	v_cmp_le_u32_e32 vcc, v152, v141
	v_cvt_f32_ubyte0_e32 v41, v107
	v_add_u32_e32 v118, 31, v107
	v_cndmask_b32_e32 v155, v244, v40, vcc
	v_cvt_f32_ubyte0_e32 v40, v103
	v_pk_add_f32 v[40:41], v[40:41], s[24:25] op_sel_hi:[1,0]
	v_or_b32_e32 v102, 31, v103
	v_pk_add_f32 v[116:117], v[52:53], v[40:41] op_sel_hi:[0,1] neg_lo:[0,1] neg_hi:[0,1]
	v_pk_fma_f32 v[26:27], v[140:141], v[116:117], v[26:27] op_sel_hi:[0,1,1] neg_lo:[1,0,0] neg_hi:[1,0,0]
	v_cmp_le_u32_e32 vcc, v118, v141
	v_lshlrev_b32_e32 v116, 4, v75
	v_lshlrev_b32_e32 v117, 4, v76
	v_cndmask_b32_e32 v103, v244, v27, vcc
	v_cmp_le_u32_e32 vcc, v102, v141
	v_cvt_f32_u32_e32 v27, v116
	v_or_b32_e32 v157, 31, v117
	v_cndmask_b32_e32 v107, v244, v26, vcc
	v_cvt_f32_u32_e32 v26, v117
	v_add_u32_e32 v158, 31, v116
	v_cmp_le_u32_e32 vcc, v158, v141
	v_max3_f32 v156, v107, s2, v103
	v_pk_add_f32 v[26:27], v[26:27], s[24:25] op_sel_hi:[1,0]
	v_cvt_f32_u32_e32 v50, v139
	v_pk_add_f32 v[116:117], v[52:53], v[26:27] op_sel_hi:[0,1] neg_lo:[0,1] neg_hi:[0,1]
	v_pk_fma_f32 v[28:29], v[140:141], v[116:117], v[28:29] op_sel_hi:[0,1,1] neg_lo:[1,0,0] neg_hi:[1,0,0]
	v_cndmask_b32_e32 v52, v244, v29, vcc
	v_cmp_le_u32_e32 vcc, v157, v141
	s_cselect_b64 s[24:25], -1, 0
	s_nop 0
	v_cndmask_b32_e32 v116, v244, v28, vcc
	v_max3_f32 v28, v156, v116, v52
	v_max3_f32 v28, v28, v151, v150
	v_max3_f32 v28, v28, v155, v154
	v_max3_f32 v28, v28, v47, v42
	v_max3_f32 v28, v28, v49, v44
	v_max3_f32 v117, v28, v100, v46
	v_pk_add_f32 v[28:29], v[50:51], v[54:55] op_sel_hi:[0,1] neg_lo:[0,1] neg_hi:[0,1]
	v_pk_fma_f32 v[28:29], v[140:141], v[28:29], v[34:35] op_sel_hi:[0,1,1] neg_lo:[1,0,0] neg_hi:[1,0,0]
	v_cmp_le_u32_e32 vcc, v120, v139
	s_nop 1
	v_cndmask_b32_e32 v34, v244, v29, vcc
	v_cmp_le_u32_e32 vcc, v121, v139
	s_nop 1
	v_cndmask_b32_e32 v35, v244, v28, vcc
	v_pk_add_f32 v[28:29], v[50:51], v[56:57] op_sel_hi:[0,1] neg_lo:[0,1] neg_hi:[0,1]
	v_pk_fma_f32 v[28:29], v[140:141], v[28:29], v[36:37] op_sel_hi:[0,1,1] neg_lo:[1,0,0] neg_hi:[1,0,0]
	v_cmp_le_u32_e32 vcc, v125, v139
	s_nop 1
	v_cndmask_b32_e32 v36, v244, v29, vcc
	v_cmp_le_u32_e32 vcc, v124, v139
	s_nop 1
	v_cndmask_b32_e32 v37, v244, v28, vcc
	v_pk_add_f32 v[28:29], v[50:51], v[58:59] op_sel_hi:[0,1] neg_lo:[0,1] neg_hi:[0,1]
	v_pk_fma_f32 v[28:29], v[140:141], v[28:29], v[30:31] op_sel_hi:[0,1,1] neg_lo:[1,0,0] neg_hi:[1,0,0]
	v_cmp_le_u32_e32 vcc, v126, v139
	s_nop 1
	v_cndmask_b32_e32 v30, v244, v29, vcc
	v_cmp_le_u32_e32 vcc, v127, v139
	s_nop 1
	v_cndmask_b32_e32 v31, v244, v28, vcc
	v_pk_add_f32 v[28:29], v[50:51], v[60:61] op_sel_hi:[0,1] neg_lo:[0,1] neg_hi:[0,1]
	v_pk_fma_f32 v[28:29], v[140:141], v[28:29], v[32:33] op_sel_hi:[0,1,1] neg_lo:[1,0,0] neg_hi:[1,0,0]
	v_cmp_le_u32_e32 vcc, v129, v139
	s_nop 1
	v_cndmask_b32_e32 v32, v244, v29, vcc
; __device__ __forceinline__ void nsa_item(const Params& p, int l, int item, lptr lds) {
;     ...
;         for (int mi = 0; mi < 2; ++mi) { const int t = trow[mi]; float mx = -1e30f;
; #pragma unroll
;             for (int ni = 0; ni < 8; ++ni)
; #pragma unroll
;                 for (int jj = 0; jj < 4; ++jj) { const int ci = ni * 16 + fq * 4 + jj; const bool valid = (16 * ci + 31 <= t);
;                     const float s = valid ? S[mi][ni][jj] - slope * ((float)t - (16.f * (float)ci + 15.5f)) : -1e30f; S[mi][ni][jj] = s; mx = fmaxf(mx, s); }
;             mx = fmaxf(mx, __shfl_xor(mx, 16)); mx = fmaxf(mx, __shfl_xor(mx, 32)); float sum = 0.f;
	v_cmp_le_u32_e32 vcc, v128, v139
	s_nop 1
	v_cndmask_b32_e32 v33, v244, v28, vcc
	v_pk_add_f32 v[28:29], v[50:51], v[62:63] op_sel_hi:[0,1] neg_lo:[0,1] neg_hi:[0,1]
	v_pk_fma_f32 v[22:23], v[140:141], v[28:29], v[22:23] op_sel_hi:[0,1,1] neg_lo:[1,0,0] neg_hi:[1,0,0]
	v_cmp_le_u32_e32 vcc, v130, v139
	s_nop 1
	v_cndmask_b32_e32 v28, v244, v23, vcc
	v_cmp_le_u32_e32 vcc, v131, v139
	s_nop 1
	v_cndmask_b32_e32 v29, v244, v22, vcc
	v_pk_add_f32 v[22:23], v[50:51], v[64:65] op_sel_hi:[0,1] neg_lo:[0,1] neg_hi:[0,1]
	v_pk_fma_f32 v[22:23], v[140:141], v[22:23], v[24:25] op_sel_hi:[0,1,1] neg_lo:[1,0,0] neg_hi:[1,0,0]
	v_cmp_le_u32_e32 vcc, v133, v139
	s_nop 1
	v_cndmask_b32_e32 v24, v244, v23, vcc
	v_cmp_le_u32_e32 vcc, v132, v139
	s_nop 1
	v_cndmask_b32_e32 v54, v244, v22, vcc
	v_pk_add_f32 v[22:23], v[50:51], v[66:67] op_sel_hi:[0,1] neg_lo:[0,1] neg_hi:[0,1]
	v_pk_fma_f32 v[18:19], v[140:141], v[22:23], v[18:19] op_sel_hi:[0,1,1] neg_lo:[1,0,0] neg_hi:[1,0,0]
	v_cmp_le_u32_e32 vcc, v134, v139
	s_nop 1
	v_cndmask_b32_e32 v22, v244, v19, vcc
	v_cmp_le_u32_e32 vcc, v135, v139
	s_nop 1
	v_cndmask_b32_e32 v23, v244, v18, vcc
	v_pk_add_f32 v[18:19], v[50:51], v[68:69] op_sel_hi:[0,1] neg_lo:[0,1] neg_hi:[0,1]
	v_pk_fma_f32 v[18:19], v[140:141], v[18:19], v[20:21] op_sel_hi:[0,1,1] neg_lo:[1,0,0] neg_hi:[1,0,0]
	v_cmp_le_u32_e32 vcc, v137, v139
	s_nop 1
	v_cndmask_b32_e32 v20, v244, v19, vcc
	v_cmp_le_u32_e32 vcc, v136, v139
	s_nop 1
	v_cndmask_b32_e32 v25, v244, v18, vcc
	v_pk_add_f32 v[18:19], v[50:51], v[104:105] op_sel_hi:[0,1] neg_lo:[0,1] neg_hi:[0,1]
	v_pk_fma_f32 v[14:15], v[140:141], v[18:19], v[14:15] op_sel_hi:[0,1,1] neg_lo:[1,0,0] neg_hi:[1,0,0]
	v_cmp_le_u32_e32 vcc, v142, v139
	s_nop 1
	v_cndmask_b32_e32 v18, v244, v15, vcc
	v_cmp_le_u32_e32 vcc, v143, v139
	s_nop 1
	v_cndmask_b32_e32 v19, v244, v14, vcc
	v_pk_add_f32 v[14:15], v[50:51], v[108:109] op_sel_hi:[0,1] neg_lo:[0,1] neg_hi:[0,1]
	v_pk_fma_f32 v[14:15], v[140:141], v[14:15], v[16:17] op_sel_hi:[0,1,1] neg_lo:[1,0,0] neg_hi:[1,0,0]
	v_cmp_le_u32_e32 vcc, v145, v139
	s_nop 1
	v_cndmask_b32_e32 v16, v244, v15, vcc
	v_cmp_le_u32_e32 vcc, v144, v139
	s_nop 1
	v_cndmask_b32_e32 v21, v244, v14, vcc
	v_pk_add_f32 v[14:15], v[50:51], v[110:111] op_sel_hi:[0,1] neg_lo:[0,1] neg_hi:[0,1]
	v_pk_fma_f32 v[10:11], v[140:141], v[14:15], v[10:11] op_sel_hi:[0,1,1] neg_lo:[1,0,0] neg_hi:[1,0,0]
	v_cmp_le_u32_e32 vcc, v146, v139
	s_nop 1
	v_cndmask_b32_e32 v14, v244, v11, vcc
	v_cmp_le_u32_e32 vcc, v147, v139
	s_nop 1
	v_cndmask_b32_e32 v15, v244, v10, vcc
	v_pk_add_f32 v[10:11], v[50:51], v[112:113] op_sel_hi:[0,1] neg_lo:[0,1] neg_hi:[0,1]
	v_pk_fma_f32 v[10:11], v[140:141], v[10:11], v[12:13] op_sel_hi:[0,1,1] neg_lo:[1,0,0] neg_hi:[1,0,0]
	v_cmp_le_u32_e32 vcc, v148, v139
	s_nop 1
	v_cndmask_b32_e32 v12, v244, v11, vcc
	v_cmp_le_u32_e32 vcc, v43, v139
	s_nop 1
	v_cndmask_b32_e32 v17, v244, v10, vcc
	v_pk_add_f32 v[10:11], v[50:51], v[114:115] op_sel_hi:[0,1] neg_lo:[0,1] neg_hi:[0,1]
	v_pk_fma_f32 v[6:7], v[140:141], v[10:11], v[6:7] op_sel_hi:[0,1,1] neg_lo:[1,0,0] neg_hi:[1,0,0]
	v_cmp_le_u32_e32 vcc, v149, v139
	s_nop 1
	v_cndmask_b32_e32 v10, v244, v7, vcc
	v_cmp_le_u32_e32 vcc, v45, v139
	s_nop 1
	v_cndmask_b32_e32 v11, v244, v6, vcc
	v_pk_add_f32 v[6:7], v[50:51], v[38:39] op_sel_hi:[0,1] neg_lo:[0,1] neg_hi:[0,1]
	v_pk_fma_f32 v[6:7], v[140:141], v[6:7], v[8:9] op_sel_hi:[0,1,1] neg_lo:[1,0,0] neg_hi:[1,0,0]
	v_cmp_le_u32_e32 vcc, v153, v139
	s_nop 1
	v_cndmask_b32_e32 v8, v244, v7, vcc
	v_cmp_le_u32_e32 vcc, v152, v139
	s_nop 1
	v_cndmask_b32_e32 v13, v244, v6, vcc
	v_pk_add_f32 v[6:7], v[50:51], v[40:41] op_sel_hi:[0,1] neg_lo:[0,1] neg_hi:[0,1]
	v_pk_fma_f32 v[2:3], v[140:141], v[6:7], v[2:3] op_sel_hi:[0,1,1] neg_lo:[1,0,0] neg_hi:[1,0,0]
	v_cmp_le_u32_e32 vcc, v118, v139
	s_nop 1
	v_cndmask_b32_e32 v6, v244, v3, vcc
	v_cmp_le_u32_e32 vcc, v102, v139
	s_nop 1
	v_cndmask_b32_e32 v7, v244, v2, vcc
	v_pk_add_f32 v[2:3], v[50:51], v[26:27] op_sel_hi:[0,1] neg_lo:[0,1] neg_hi:[0,1]
	v_pk_fma_f32 v[2:3], v[140:141], v[2:3], v[4:5] op_sel_hi:[0,1,1] neg_lo:[1,0,0] neg_hi:[1,0,0]
	v_cmp_le_u32_e32 vcc, v158, v139
	v_max3_f32 v9, v7, s2, v6
	v_max3_f32 v5, v117, v101, v48
	v_cndmask_b32_e32 v4, v244, v3, vcc
	v_cmp_le_u32_e32 vcc, v157, v139
	v_max3_f32 v5, v5, v53, v51
	v_max3_f32 v5, v5, v99, v98
	v_cndmask_b32_e32 v26, v244, v2, vcc
	v_max3_f32 v2, v9, v26, v4
	v_max3_f32 v2, v2, v11, v10
	v_max3_f32 v2, v2, v13, v8
	v_max3_f32 v2, v2, v15, v14
	v_max3_f32 v2, v2, v17, v12
	v_max3_f32 v2, v2, v19, v18
	v_max3_f32 v2, v2, v21, v16
	v_max3_f32 v2, v2, v23, v22
	v_max3_f32 v2, v2, v25, v20
	v_max3_f32 v2, v2, v29, v28
	v_max3_f32 v2, v2, v54, v24
	v_max3_f32 v2, v2, v31, v30
	v_max3_f32 v2, v2, v33, v32
	v_max3_f32 v2, v2, v35, v34
	v_max3_f32 v2, v2, v37, v36
	ds_bpermute_b32 v3, v172, v2
	v_max3_f32 v5, v5, v95, v94
	v_max3_f32 v5, v5, v97, v96
	v_max3_f32 v5, v5, v91, v83
	v_max3_f32 v5, v5, v93, v92
	s_waitcnt lgkmcnt(0)
	v_max_f32_e32 v3, v3, v3
	v_max_f32_e32 v2, v2, v3
	ds_bpermute_b32 v3, v173, v2
	v_max3_f32 v38, v5, v72, v70
	s_mov_b32 s2, 0xefa18f08
	v_cmp_lt_f32_e32 vcc, s2, v6
	s_waitcnt lgkmcnt(0)
; __device__ __forceinline__ void nsa_item(const Params& p, int l, int item, lptr lds) {
;     ...
;             mx = fmaxf(mx, __shfl_xor(mx, 16)); mx = fmaxf(mx, __shfl_xor(mx, 32)); float sum = 0.f;
; #pragma unroll
;             for (int ni = 0; ni < 8; ++ni)
; #pragma unroll
;                 for (int jj = 0; jj < 4; ++jj) { const float s = S[mi][ni][jj]; const float pv = s > -1e29f ? __builtin_amdgcn_exp2f(s - mx) : 0.f; S[mi][ni][jj] = pv; sum += pv; }
	v_max_f32_e32 v3, v3, v3
	v_max_f32_e32 v39, v2, v3
	v_sub_f32_e32 v2, v6, v39
	v_exp_f32_e32 v2, v2
	v_sub_f32_e32 v3, v7, v39
	v_exp_f32_e32 v5, v3
	v_sub_f32_e32 v6, v26, v39
	v_cndmask_b32_e32 v3, 0, v2, vcc
	v_cmp_lt_f32_e32 vcc, s2, v7
	v_exp_f32_e32 v6, v6
	v_sub_f32_e32 v7, v11, v39
	v_cndmask_b32_e32 v2, 0, v5, vcc
	v_sub_f32_e32 v5, v4, v39
	v_exp_f32_e32 v5, v5
	v_cmp_lt_f32_e32 vcc, s2, v4
	v_exp_f32_e32 v9, v7
	v_sub_f32_e32 v27, v31, v39
	v_cndmask_b32_e32 v5, 0, v5, vcc
	v_cmp_lt_f32_e32 vcc, s2, v26
	v_sub_f32_e32 v26, v54, v39
	v_exp_f32_e32 v26, v26
	v_cndmask_b32_e32 v4, 0, v6, vcc
	v_sub_f32_e32 v6, v10, v39
	v_exp_f32_e32 v6, v6
	v_cmp_lt_f32_e32 vcc, s2, v10
	v_sub_f32_e32 v10, v13, v39
	v_exp_f32_e32 v10, v10
	v_cndmask_b32_e32 v7, 0, v6, vcc
	v_cmp_lt_f32_e32 vcc, s2, v11
	v_sub_f32_e32 v11, v15, v39
	v_mov_b32_e32 v57, v3
	v_cndmask_b32_e32 v6, 0, v9, vcc
	v_sub_f32_e32 v9, v8, v39
	v_exp_f32_e32 v9, v9
	v_cmp_lt_f32_e32 vcc, s2, v8
	s_nop 1
	v_cndmask_b32_e32 v9, 0, v9, vcc
	v_cmp_lt_f32_e32 vcc, s2, v13
	v_exp_f32_e32 v13, v11
	s_nop 0
	v_cndmask_b32_e32 v8, 0, v10, vcc
	v_sub_f32_e32 v10, v14, v39
	v_exp_f32_e32 v10, v10
	v_cmp_lt_f32_e32 vcc, s2, v14
	v_sub_f32_e32 v14, v17, v39
	v_exp_f32_e32 v14, v14
	v_cndmask_b32_e32 v11, 0, v10, vcc
	v_cmp_lt_f32_e32 vcc, s2, v15
	v_sub_f32_e32 v15, v19, v39
	s_nop 0
	v_cndmask_b32_e32 v10, 0, v13, vcc
	v_sub_f32_e32 v13, v12, v39
	v_exp_f32_e32 v13, v13
	v_cmp_lt_f32_e32 vcc, s2, v12
	s_nop 1
	v_cndmask_b32_e32 v13, 0, v13, vcc
	v_cmp_lt_f32_e32 vcc, s2, v17
	v_exp_f32_e32 v17, v15
	s_nop 0
	v_cndmask_b32_e32 v12, 0, v14, vcc
	v_sub_f32_e32 v14, v18, v39
	v_exp_f32_e32 v14, v14
	v_cmp_lt_f32_e32 vcc, s2, v18
	v_sub_f32_e32 v18, v21, v39
	v_exp_f32_e32 v18, v18
	v_cndmask_b32_e32 v15, 0, v14, vcc
	v_cmp_lt_f32_e32 vcc, s2, v19
	v_sub_f32_e32 v19, v23, v39
	s_nop 0
	v_cndmask_b32_e32 v14, 0, v17, vcc
	v_sub_f32_e32 v17, v16, v39
	v_exp_f32_e32 v17, v17
	v_cmp_lt_f32_e32 vcc, s2, v16
	v_mov_b32_e32 v61, v14
	s_nop 0
	v_cndmask_b32_e32 v17, 0, v17, vcc
	v_cmp_lt_f32_e32 vcc, s2, v21
	v_exp_f32_e32 v21, v19
	s_nop 0
	v_cndmask_b32_e32 v16, 0, v18, vcc
	v_sub_f32_e32 v18, v22, v39
	v_exp_f32_e32 v18, v18
	v_cmp_lt_f32_e32 vcc, s2, v22
	v_sub_f32_e32 v22, v25, v39
	v_exp_f32_e32 v22, v22
	v_cndmask_b32_e32 v19, 0, v18, vcc
	v_cmp_lt_f32_e32 vcc, s2, v23
	v_sub_f32_e32 v23, v29, v39
	s_nop 0
	v_cndmask_b32_e32 v18, 0, v21, vcc
	v_sub_f32_e32 v21, v20, v39
	v_exp_f32_e32 v21, v21
	v_cmp_lt_f32_e32 vcc, s2, v20
	s_nop 1
	v_cndmask_b32_e32 v21, 0, v21, vcc
	v_cmp_lt_f32_e32 vcc, s2, v25
	v_exp_f32_e32 v25, v23
	s_nop 0
	v_cndmask_b32_e32 v20, 0, v22, vcc
	v_sub_f32_e32 v22, v28, v39
	v_exp_f32_e32 v22, v22
	v_cmp_lt_f32_e32 vcc, s2, v28
	v_exp_f32_e32 v28, v27
	s_nop 0
	v_cndmask_b32_e32 v23, 0, v22, vcc
	v_cmp_lt_f32_e32 vcc, s2, v29
	v_sub_f32_e32 v29, v33, v39
	s_nop 0
	v_cndmask_b32_e32 v22, 0, v25, vcc
	v_sub_f32_e32 v25, v24, v39
	v_exp_f32_e32 v25, v25
	v_cmp_lt_f32_e32 vcc, s2, v24
	s_nop 1
	v_cndmask_b32_e32 v25, 0, v25, vcc
	v_cmp_lt_f32_e32 vcc, s2, v54
	v_mov_b32_e32 v69, v25
	s_nop 0
	v_cndmask_b32_e32 v24, 0, v26, vcc
	v_sub_f32_e32 v26, v30, v39
	v_exp_f32_e32 v26, v26
	v_cmp_lt_f32_e32 vcc, s2, v30
	v_exp_f32_e32 v30, v29
	s_nop 0
	v_cndmask_b32_e32 v27, 0, v26, vcc
	v_cmp_lt_f32_e32 vcc, s2, v31
	v_sub_f32_e32 v31, v35, v39
	s_nop 0
	v_cndmask_b32_e32 v26, 0, v28, vcc
	v_sub_f32_e32 v28, v32, v39
	v_exp_f32_e32 v28, v28
	v_cmp_lt_f32_e32 vcc, s2, v32
	v_exp_f32_e32 v32, v31
	s_nop 0
	v_cndmask_b32_e32 v29, 0, v28, vcc
	v_cmp_lt_f32_e32 vcc, s2, v33
	s_nop 1
	v_cndmask_b32_e32 v28, 0, v30, vcc
	v_sub_f32_e32 v30, v34, v39
	v_exp_f32_e32 v30, v30
	v_cmp_lt_f32_e32 vcc, s2, v34
	v_sub_f32_e32 v34, v37, v39
	v_exp_f32_e32 v34, v34
	v_cndmask_b32_e32 v31, 0, v30, vcc
	v_cmp_lt_f32_e32 vcc, s2, v35
	v_sub_f32_e32 v35, v36, v39
	v_exp_f32_e32 v35, v35
	v_cndmask_b32_e32 v30, 0, v32, vcc
	v_max3_f32 v32, v38, v73, v71
	ds_bpermute_b32 v33, v172, v32
	v_cmp_lt_f32_e32 vcc, s2, v36
	s_waitcnt lgkmcnt(0)
	v_max_f32_e32 v33, v33, v33
	v_max_f32_e32 v38, v32, v33
	ds_bpermute_b32 v39, v173, v38
	v_cndmask_b32_e32 v33, 0, v35, vcc
	v_cmp_lt_f32_e32 vcc, s2, v37
	v_mov_b32_e32 v37, v2
	s_nop 0
	v_cndmask_b32_e32 v32, 0, v34, vcc
	s_waitcnt lgkmcnt(0)
	v_max_f32_e32 v34, v39, v39
	v_max_f32_e32 v64, v38, v34
	v_sub_f32_e32 v34, v103, v64
	v_exp_f32_e32 v34, v34
	v_sub_f32_e32 v35, v107, v64
	v_exp_f32_e32 v36, v35
	v_cmp_lt_f32_e32 vcc, s2, v103
	v_sub_f32_e32 v39, v151, v64
	v_exp_f32_e32 v40, v39
	v_cndmask_b32_e32 v35, 0, v34, vcc
	v_cmp_lt_f32_e32 vcc, s2, v107
	v_sub_f32_e32 v41, v155, v64
	v_exp_f32_e32 v43, v41
	v_cndmask_b32_e32 v34, 0, v36, vcc
	v_mov_b32_e32 v36, v34
	v_pk_add_f32 v[54:55], v[36:37], 0 op_sel_hi:[1,0]
	v_sub_f32_e32 v36, v52, v64
	v_exp_f32_e32 v36, v36
	v_sub_f32_e32 v37, v116, v64
	v_exp_f32_e32 v38, v37
	v_cmp_lt_f32_e32 vcc, s2, v52
	v_sub_f32_e32 v45, v47, v64
	v_exp_f32_e32 v45, v45
	v_cndmask_b32_e32 v37, 0, v36, vcc
	v_cmp_lt_f32_e32 vcc, s2, v116
	v_sub_f32_e32 v50, v101, v64
	v_exp_f32_e32 v50, v50
	v_cndmask_b32_e32 v36, 0, v38, vcc
	v_sub_f32_e32 v38, v150, v64
	v_exp_f32_e32 v38, v38
	v_cmp_lt_f32_e32 vcc, s2, v150
	v_mov_b32_e32 v56, v35
	v_pk_add_f32 v[54:55], v[56:57], v[54:55]
	v_cndmask_b32_e32 v39, 0, v38, vcc
	v_cmp_lt_f32_e32 vcc, s2, v151
	v_mov_b32_e32 v56, v36
	v_mov_b32_e32 v57, v4
	v_cndmask_b32_e32 v38, 0, v40, vcc
	v_sub_f32_e32 v40, v154, v64
	v_exp_f32_e32 v40, v40
	v_cmp_lt_f32_e32 vcc, s2, v154
	v_pk_add_f32 v[54:55], v[56:57], v[54:55]
	v_mov_b32_e32 v56, v37
	v_cndmask_b32_e32 v41, 0, v40, vcc
	v_cmp_lt_f32_e32 vcc, s2, v155
	v_mov_b32_e32 v57, v5
	v_pk_add_f32 v[54:55], v[56:57], v[54:55]
	v_cndmask_b32_e32 v40, 0, v43, vcc
	v_sub_f32_e32 v43, v42, v64
	v_exp_f32_e32 v43, v43
	v_cmp_lt_f32_e32 vcc, s2, v42
	v_mov_b32_e32 v56, v38
	v_mov_b32_e32 v57, v6
	v_cndmask_b32_e32 v43, 0, v43, vcc
	v_cmp_lt_f32_e32 vcc, s2, v47
	v_sub_f32_e32 v47, v49, v64
	v_exp_f32_e32 v47, v47
	v_cndmask_b32_e32 v42, 0, v45, vcc
	v_sub_f32_e32 v45, v44, v64
	v_exp_f32_e32 v45, v45
	v_cmp_lt_f32_e32 vcc, s2, v44
	v_pk_add_f32 v[54:55], v[56:57], v[54:55]
	v_mov_b32_e32 v56, v39
	v_cndmask_b32_e32 v45, 0, v45, vcc
	v_cmp_lt_f32_e32 vcc, s2, v49
	v_sub_f32_e32 v49, v100, v64
	v_exp_f32_e32 v49, v49
	v_cndmask_b32_e32 v44, 0, v47, vcc
	v_sub_f32_e32 v47, v46, v64
	v_exp_f32_e32 v47, v47
	v_cmp_lt_f32_e32 vcc, s2, v46
	v_mov_b32_e32 v57, v7
	v_sub_f32_e32 v52, v53, v64
	v_cndmask_b32_e32 v47, 0, v47, vcc
	v_cmp_lt_f32_e32 vcc, s2, v100
	v_pk_add_f32 v[54:55], v[56:57], v[54:55]
	v_mov_b32_e32 v56, v40
	v_cndmask_b32_e32 v46, 0, v49, vcc
	v_sub_f32_e32 v49, v48, v64
	v_exp_f32_e32 v49, v49
	v_cmp_lt_f32_e32 vcc, s2, v48
	v_mov_b32_e32 v57, v8
	v_exp_f32_e32 v52, v52
	v_cndmask_b32_e32 v49, 0, v49, vcc
	v_cmp_lt_f32_e32 vcc, s2, v101
	v_pk_add_f32 v[54:55], v[56:57], v[54:55]
	v_mov_b32_e32 v56, v41
	v_cndmask_b32_e32 v48, 0, v50, vcc
	v_sub_f32_e32 v50, v51, v64
	v_exp_f32_e32 v50, v50
	v_mov_b32_e32 v57, v9
	v_pk_add_f32 v[54:55], v[56:57], v[54:55]
	v_mov_b32_e32 v56, v42
	v_mov_b32_e32 v57, v10
	v_cmp_lt_f32_e32 vcc, s2, v51
	v_pk_add_f32 v[54:55], v[56:57], v[54:55]
	v_mov_b32_e32 v56, v43
	v_mov_b32_e32 v57, v11
	v_cndmask_b32_e32 v51, 0, v50, vcc
	v_cmp_lt_f32_e32 vcc, s2, v53
	v_pk_add_f32 v[54:55], v[56:57], v[54:55]
	v_mov_b32_e32 v56, v44
	v_mov_b32_e32 v57, v12
	v_cndmask_b32_e32 v50, 0, v52, vcc
	v_sub_f32_e32 v52, v98, v64
	v_pk_add_f32 v[54:55], v[56:57], v[54:55]
	v_mov_b32_e32 v56, v45
	v_mov_b32_e32 v57, v13
	v_exp_f32_e32 v52, v52
	v_sub_f32_e32 v53, v99, v64
	v_pk_add_f32 v[56:57], v[56:57], v[54:55]
	v_exp_f32_e32 v54, v53
	v_cmp_lt_f32_e32 vcc, s2, v98
	v_sub_f32_e32 v55, v95, v64
	v_exp_f32_e32 v58, v55
	v_cndmask_b32_e32 v53, 0, v52, vcc
	v_cmp_lt_f32_e32 vcc, s2, v99
	v_sub_f32_e32 v59, v97, v64
	v_exp_f32_e32 v60, v59
	v_cndmask_b32_e32 v52, 0, v54, vcc
	v_sub_f32_e32 v54, v94, v64
	v_exp_f32_e32 v54, v54
	v_cmp_lt_f32_e32 vcc, s2, v94
	v_sub_f32_e32 v66, v72, v64
	v_exp_f32_e32 v66, v66
	v_cndmask_b32_e32 v55, 0, v54, vcc
	v_cmp_lt_f32_e32 vcc, s2, v95
	s_nop 1
	v_cndmask_b32_e32 v54, 0, v58, vcc
	v_sub_f32_e32 v58, v96, v64
	v_exp_f32_e32 v58, v58
	v_cmp_lt_f32_e32 vcc, s2, v96
	s_nop 1
	v_cndmask_b32_e32 v59, 0, v58, vcc
	v_cmp_lt_f32_e32 vcc, s2, v97
	v_mov_b32_e32 v68, v59
	s_nop 0
	v_cndmask_b32_e32 v58, 0, v60, vcc
	v_mov_b32_e32 v60, v46
	v_pk_add_f32 v[56:57], v[60:61], v[56:57]
	v_mov_b32_e32 v60, v47
	v_mov_b32_e32 v61, v15
	v_pk_add_f32 v[56:57], v[60:61], v[56:57]
	v_mov_b32_e32 v60, v48
	v_mov_b32_e32 v61, v16
	v_pk_add_f32 v[56:57], v[60:61], v[56:57]
	v_mov_b32_e32 v60, v49
	v_mov_b32_e32 v61, v17
	v_pk_add_f32 v[56:57], v[60:61], v[56:57]
	v_mov_b32_e32 v60, v50
	v_mov_b32_e32 v61, v18
	v_pk_add_f32 v[56:57], v[60:61], v[56:57]
	v_mov_b32_e32 v60, v51
	v_mov_b32_e32 v61, v19
	v_pk_add_f32 v[56:57], v[60:61], v[56:57]
	v_mov_b32_e32 v60, v52
	v_mov_b32_e32 v61, v20
	v_pk_add_f32 v[56:57], v[60:61], v[56:57]
	v_mov_b32_e32 v60, v53
	v_mov_b32_e32 v61, v21
	v_pk_add_f32 v[56:57], v[60:61], v[56:57]
	v_mov_b32_e32 v60, v54
	v_mov_b32_e32 v61, v22
	v_pk_add_f32 v[56:57], v[60:61], v[56:57]
	v_mov_b32_e32 v60, v55
	v_mov_b32_e32 v61, v23
	v_pk_add_f32 v[56:57], v[60:61], v[56:57]
	v_mov_b32_e32 v60, v58
	v_mov_b32_e32 v61, v24
	v_pk_add_f32 v[56:57], v[60:61], v[56:57]
	v_sub_f32_e32 v60, v83, v64
	v_exp_f32_e32 v60, v60
	v_sub_f32_e32 v61, v91, v64
	v_exp_f32_e32 v61, v61
	v_cmp_lt_f32_e32 vcc, s2, v83
	v_pk_add_f32 v[56:57], v[68:69], v[56:57]
	v_mov_b32_e32 v69, v26
	v_cndmask_b32_e32 v63, 0, v60, vcc
	v_cmp_lt_f32_e32 vcc, s2, v91
	v_sub_f32_e32 v60, v92, v64
	v_exp_f32_e32 v60, v60
	v_cndmask_b32_e32 v62, 0, v61, vcc
	v_sub_f32_e32 v61, v93, v64
	v_exp_f32_e32 v65, v61
	v_cmp_lt_f32_e32 vcc, s2, v92
	v_mov_b32_e32 v68, v62
	v_pk_add_f32 v[56:57], v[68:69], v[56:57]
	v_cndmask_b32_e32 v61, 0, v60, vcc
	v_cmp_lt_f32_e32 vcc, s2, v93
	v_mov_b32_e32 v68, v63
	v_mov_b32_e32 v69, v27
	v_cndmask_b32_e32 v60, 0, v65, vcc
	v_sub_f32_e32 v65, v70, v64
	v_exp_f32_e32 v65, v65
	v_cmp_lt_f32_e32 vcc, s2, v70
	v_pk_add_f32 v[56:57], v[68:69], v[56:57]
	v_mov_b32_e32 v68, v60
	v_cndmask_b32_e32 v67, 0, v65, vcc
	v_sub_f32_e32 v65, v71, v64
	v_exp_f32_e32 v65, v65
	v_sub_f32_e32 v64, v73, v64
	v_exp_f32_e32 v64, v64
	v_cmp_lt_f32_e32 vcc, s2, v72
	v_mov_b32_e32 v69, v28
	v_pk_add_f32 v[56:57], v[68:69], v[56:57]
	v_cndmask_b32_e32 v66, 0, v66, vcc
	v_cmp_lt_f32_e32 vcc, s2, v71
	v_mov_b32_e32 v68, v61
	v_mov_b32_e32 v69, v29
	v_cndmask_b32_e32 v65, 0, v65, vcc
	v_cmp_lt_f32_e32 vcc, s2, v73
	v_pk_add_f32 v[56:57], v[68:69], v[56:57]
	v_mov_b32_e32 v68, v66
	v_mov_b32_e32 v69, v30
	v_cndmask_b32_e32 v64, 0, v64, vcc
	v_pk_add_f32 v[56:57], v[68:69], v[56:57]
	v_mov_b32_e32 v68, v67
	v_mov_b32_e32 v69, v31
	v_pk_add_f32 v[56:57], v[68:69], v[56:57]
	v_mov_b32_e32 v68, v64
	v_mov_b32_e32 v69, v32
	v_pk_add_f32 v[56:57], v[68:69], v[56:57]
	v_mov_b32_e32 v68, v65
	v_mov_b32_e32 v69, v33
	v_pk_add_f32 v[56:57], v[68:69], v[56:57]
	ds_bpermute_b32 v69, v172, v57
	ds_bpermute_b32 v68, v172, v56
	v_and_b32_e32 v83, 63, v77
	s_waitcnt lgkmcnt(0)
	v_pk_add_f32 v[56:57], v[56:57], v[68:69]
	ds_bpermute_b32 v69, v173, v57
	ds_bpermute_b32 v68, v173, v56
	s_waitcnt lgkmcnt(0)
	v_pk_add_f32 v[56:57], v[56:57], v[68:69]
	s_nop 0
	v_div_scale_f32 v68, s[2:3], v57, v57, 1.0
	v_rcp_f32_e32 v69, v68
	s_nop 0
	v_fma_f32 v70, -v68, v69, 1.0
	v_fmac_f32_e32 v69, v70, v69
	v_div_scale_f32 v70, vcc, 1.0, v57, 1.0
	v_mul_f32_e32 v71, v70, v69
	v_fma_f32 v72, -v68, v71, v70
	v_fmac_f32_e32 v71, v72, v69
	v_fma_f32 v68, -v68, v71, v70
	v_div_fmas_f32 v68, v68, v69, v71
	v_div_fixup_f32 v68, v68, v57, 1.0
	v_cmp_lt_f32_e32 vcc, 0, v57
	v_div_scale_f32 v57, s[2:3], v56, v56, 1.0
	s_nop 0
	v_cndmask_b32_e32 v68, 0, v68, vcc
	v_pk_mul_f32 v[4:5], v[4:5], v[68:69] op_sel_hi:[1,0]
	v_pk_mul_f32 v[2:3], v[2:3], v[68:69] op_sel_hi:[1,0]
	v_pk_mul_f32 v[8:9], v[8:9], v[68:69] op_sel_hi:[1,0]
	v_pk_mul_f32 v[6:7], v[6:7], v[68:69] op_sel_hi:[1,0]
	v_pk_mul_f32 v[12:13], v[12:13], v[68:69] op_sel_hi:[1,0]
	v_pk_mul_f32 v[10:11], v[10:11], v[68:69] op_sel_hi:[1,0]
	v_pk_mul_f32 v[16:17], v[16:17], v[68:69] op_sel_hi:[1,0]
	v_pk_mul_f32 v[14:15], v[14:15], v[68:69] op_sel_hi:[1,0]
	v_pk_mul_f32 v[20:21], v[20:21], v[68:69] op_sel_hi:[1,0]
	v_pk_mul_f32 v[18:19], v[18:19], v[68:69] op_sel_hi:[1,0]
	v_pk_mul_f32 v[24:25], v[24:25], v[68:69] op_sel_hi:[1,0]
	v_pk_mul_f32 v[22:23], v[22:23], v[68:69] op_sel_hi:[1,0]
	v_pk_mul_f32 v[28:29], v[28:29], v[68:69] op_sel_hi:[1,0]
	v_rcp_f32_e32 v69, v57
	s_nop 0
	v_pk_mul_f32 v[26:27], v[26:27], v[68:69] op_sel_hi:[1,0]
	v_pk_mul_f32 v[32:33], v[32:33], v[68:69] op_sel_hi:[1,0]
	v_pk_mul_f32 v[30:31], v[30:31], v[68:69] op_sel_hi:[1,0]
	v_fma_f32 v68, -v57, v69, 1.0
	v_fmac_f32_e32 v69, v68, v69
	v_div_scale_f32 v68, vcc, 1.0, v56, 1.0
	v_mul_f32_e32 v70, v68, v69
	v_fma_f32 v71, -v57, v70, v68
	v_fmac_f32_e32 v70, v71, v69
	v_fma_f32 v57, -v57, v70, v68
	v_div_fmas_f32 v57, v57, v69, v70
	v_div_fixup_f32 v57, v57, v56, 1.0
	v_cmp_lt_f32_e32 vcc, 0, v56
	s_nop 1
	v_cndmask_b32_e32 v68, 0, v57, vcc
	v_pk_mul_f32 v[56:57], v[58:59], v[68:69] op_sel_hi:[1,0]
	v_pk_mul_f32 v[58:59], v[62:63], v[68:69] op_sel_hi:[1,0]
	v_pk_mul_f32 v[62:63], v[66:67], v[68:69] op_sel_hi:[1,0]
	v_or_b32_e32 v66, s39, v119
	v_mul_u32_u24_e32 v66, 0x210, v66
	v_pk_mul_f32 v[36:37], v[36:37], v[68:69] op_sel_hi:[1,0]
	v_pk_mul_f32 v[34:35], v[34:35], v[68:69] op_sel_hi:[1,0]
	v_pk_mul_f32 v[40:41], v[40:41], v[68:69] op_sel_hi:[1,0]
	v_pk_mul_f32 v[38:39], v[38:39], v[68:69] op_sel_hi:[1,0]
	v_pk_mul_f32 v[44:45], v[44:45], v[68:69] op_sel_hi:[1,0]
	v_pk_mul_f32 v[42:43], v[42:43], v[68:69] op_sel_hi:[1,0]
	v_pk_mul_f32 v[48:49], v[48:49], v[68:69] op_sel_hi:[1,0]
	v_pk_mul_f32 v[46:47], v[46:47], v[68:69] op_sel_hi:[1,0]
	v_pk_mul_f32 v[52:53], v[52:53], v[68:69] op_sel_hi:[1,0]
	v_pk_mul_f32 v[50:51], v[50:51], v[68:69] op_sel_hi:[1,0]
	v_pk_mul_f32 v[54:55], v[54:55], v[68:69] op_sel_hi:[1,0]
	v_pk_mul_f32 v[60:61], v[60:61], v[68:69] op_sel_hi:[1,0]
	v_pk_mul_f32 v[64:65], v[64:65], v[68:69] op_sel_hi:[1,0]
	v_add_u32_e32 v0, v0, v66
	s_branch .LBB0_1891

.LBB0_1933:
	s_movk_i32 s2, 0x2000
	s_waitcnt vmcnt(1)
	v_add_co_u32_e32 v74, vcc, s2, v152
	v_lshlrev_b32_e32 v76, 16, v210
	s_nop 0
	v_addc_co_u32_e32 v75, vcc, 0, v153, vcc
	global_load_ushort v77, v[74:75], off offset:1556
	v_lshlrev_b32_e32 v74, 16, v211
	v_lshlrev_b32_e32 v75, 16, v174
	s_waitcnt vmcnt(1)
	v_mul_f32_e32 v78, 0xbfb8aa3b, v74
	v_add_co_u32_e32 v74, vcc, s2, v150
	v_mul_f32_e32 v79, 0xbfb8aa3b, v75
	s_nop 0
	v_addc_co_u32_e32 v75, vcc, 0, v151, vcc
	global_load_ushort v75, v[74:75], off offset:1556
	v_exp_f32_e32 v78, v78
	v_exp_f32_e32 v79, v79
	v_mul_f32_e32 v76, 0xbfb8aa3b, v76
	v_exp_f32_e32 v76, v76
	v_add_f32_e32 v74, 1.0, v78
	v_add_f32_e32 v78, 1.0, v79
	v_rcp_f32_e32 v79, v74
	v_add_f32_e32 v76, 1.0, v76
	v_rcp_f32_e32 v74, v78
	v_rcp_f32_e32 v78, v76
	v_div_scale_f32 v76, s[2:3], v142, v142, v79
	v_rcp_f32_e32 v106, v76
	v_lshlrev_b32_e32 v0, 16, v175
	v_mul_f32_e32 v0, 0xbfb8aa3b, v0
	v_exp_f32_e32 v0, v0
	v_fma_f32 v109, -v76, v106, 1.0
	v_div_scale_f32 v80, vcc, v79, v142, v79
	v_fmac_f32_e32 v106, v109, v106
	v_mul_f32_e32 v109, v80, v106
	v_fma_f32 v111, -v76, v109, v80
	v_add_f32_e32 v0, 1.0, v0
	v_fmac_f32_e32 v109, v111, v106
	v_rcp_f32_e32 v0, v0
	v_fma_f32 v76, -v76, v109, v80
	v_div_scale_f32 v81, s[2:3], v143, v143, v78
	v_div_fmas_f32 v76, v76, v106, v109
	v_rcp_f32_e32 v107, v81
	v_div_fixup_f32 v76, v76, v142, v79
	v_div_scale_f32 v108, s[2:3], v78, v143, v78
	v_fma_f32 v110, -v81, v107, 1.0
	v_fmac_f32_e32 v107, v110, v107
	v_mul_f32_e32 v110, v108, v107
	v_fma_f32 v112, -v81, v110, v108
	v_fmac_f32_e32 v110, v112, v107
	v_fma_f32 v80, -v81, v110, v108
	s_mov_b64 vcc, s[2:3]
	v_div_fmas_f32 v79, v80, v107, v110
	v_readlane_b32 s28, v254, 61
	v_readlane_b32 s29, v254, 62
	s_mov_b64 s[24:25], 0x17900800
	v_readlane_b32 s50, v254, 15
	v_readlane_b32 s51, v254, 16
	s_waitcnt vmcnt(1)
	v_pk_mul_f32 v[48:49], v[48:49], v[76:77] op_sel_hi:[1,0]
	v_pk_mul_f32 v[46:47], v[46:47], v[76:77] op_sel_hi:[1,0]
	v_pk_mul_f32 v[44:45], v[44:45], v[76:77] op_sel_hi:[1,0]
	v_pk_mul_f32 v[42:43], v[42:43], v[76:77] op_sel_hi:[1,0]
	v_pk_mul_f32 v[40:41], v[40:41], v[76:77] op_sel_hi:[1,0]
	v_pk_mul_f32 v[38:39], v[38:39], v[76:77] op_sel_hi:[1,0]
	v_pk_mul_f32 v[36:37], v[36:37], v[76:77] op_sel_hi:[1,0]
	v_pk_mul_f32 v[34:35], v[34:35], v[76:77] op_sel_hi:[1,0]
	v_pk_fma_f32 v[30:31], v[30:31], v[0:1], v[46:47] op_sel_hi:[1,0,1]
	v_pk_fma_f32 v[32:33], v[32:33], v[0:1], v[48:49] op_sel_hi:[1,0,1]
	v_pk_fma_f32 v[22:23], v[22:23], v[0:1], v[42:43] op_sel_hi:[1,0,1]
	v_pk_fma_f32 v[24:25], v[24:25], v[0:1], v[44:45] op_sel_hi:[1,0,1]
	v_pk_fma_f32 v[18:19], v[18:19], v[0:1], v[38:39] op_sel_hi:[1,0,1]
	v_pk_fma_f32 v[20:21], v[20:21], v[0:1], v[40:41] op_sel_hi:[1,0,1]
	v_pk_fma_f32 v[6:7], v[6:7], v[0:1], v[34:35] op_sel_hi:[1,0,1]
	v_pk_fma_f32 v[8:9], v[8:9], v[0:1], v[36:37] op_sel_hi:[1,0,1]
	v_lshlrev_b32_e32 v0, 16, v77
	v_mul_f32_e32 v0, 0xbfb8aa3b, v0
	v_exp_f32_e32 v0, v0
	v_div_fixup_f32 v76, v79, v143, v78
	v_pk_mul_f32 v[34:35], v[64:65], v[76:77] op_sel_hi:[1,0]
	v_pk_mul_f32 v[36:37], v[62:63], v[76:77] op_sel_hi:[1,0]
	v_add_f32_e32 v0, 1.0, v0
	v_rcp_f32_e32 v0, v0
	s_waitcnt vmcnt(0)
	v_pk_fma_f32 v[28:29], v[28:29], v[74:75], v[34:35] op_sel_hi:[1,0,1]
	v_pk_fma_f32 v[26:27], v[26:27], v[74:75], v[36:37] op_sel_hi:[1,0,1]
	v_pk_mul_f32 v[38:39], v[60:61], v[76:77] op_sel_hi:[1,0]
	v_div_scale_f32 v34, s[2:3], v149, v149, v0
	v_rcp_f32_e32 v35, v34
	v_pk_fma_f32 v[16:17], v[16:17], v[74:75], v[38:39] op_sel_hi:[1,0,1]
	v_pk_mul_f32 v[40:41], v[58:59], v[76:77] op_sel_hi:[1,0]
	v_pk_mul_f32 v[42:43], v[56:57], v[76:77] op_sel_hi:[1,0]
	v_fma_f32 v36, -v34, v35, 1.0
	v_fmac_f32_e32 v35, v36, v35
	v_div_scale_f32 v36, vcc, v0, v149, v0
	v_mul_f32_e32 v37, v36, v35
	v_fma_f32 v38, -v34, v37, v36
	v_fmac_f32_e32 v37, v38, v35
	v_fma_f32 v34, -v34, v37, v36
	v_div_fmas_f32 v34, v34, v35, v37
	v_div_fixup_f32 v0, v34, v149, v0
	v_lshlrev_b32_e32 v34, 16, v75
	v_mul_f32_e32 v34, 0xbfb8aa3b, v34
	v_exp_f32_e32 v34, v34
	v_pk_mul_f32 v[44:45], v[54:55], v[76:77] op_sel_hi:[1,0]
	v_pk_mul_f32 v[46:47], v[52:53], v[76:77] op_sel_hi:[1,0]
	v_pk_mul_f32 v[48:49], v[50:51], v[76:77] op_sel_hi:[1,0]
	v_add_f32_e32 v34, 1.0, v34
	v_rcp_f32_e32 v34, v34
	v_pk_fma_f32 v[14:15], v[14:15], v[74:75], v[40:41] op_sel_hi:[1,0,1]
	v_pk_fma_f32 v[10:11], v[10:11], v[74:75], v[44:45] op_sel_hi:[1,0,1]
	v_pk_fma_f32 v[12:13], v[12:13], v[74:75], v[42:43] op_sel_hi:[1,0,1]
	v_div_scale_f32 v35, s[2:3], v148, v148, v34
	v_rcp_f32_e32 v36, v35
	v_pk_fma_f32 v[2:3], v[2:3], v[74:75], v[48:49] op_sel_hi:[1,0,1]
	v_pk_fma_f32 v[4:5], v[4:5], v[74:75], v[46:47] op_sel_hi:[1,0,1]
	v_pk_fma_f32 v[2:3], v[90:91], v[0:1], v[2:3] op_sel_hi:[1,0,1]
	v_pk_fma_f32 v[4:5], v[92:93], v[0:1], v[4:5] op_sel_hi:[1,0,1]
	v_pk_fma_f32 v[12:13], v[96:97], v[0:1], v[12:13] op_sel_hi:[1,0,1]
	v_pk_fma_f32 v[10:11], v[94:95], v[0:1], v[10:11] op_sel_hi:[1,0,1]
	v_pk_fma_f32 v[16:17], v[100:101], v[0:1], v[16:17] op_sel_hi:[1,0,1]
	v_pk_fma_f32 v[14:15], v[98:99], v[0:1], v[14:15] op_sel_hi:[1,0,1]
	v_pk_fma_f32 v[28:29], v[104:105], v[0:1], v[28:29] op_sel_hi:[1,0,1]
	v_pk_fma_f32 v[26:27], v[102:103], v[0:1], v[26:27] op_sel_hi:[1,0,1]
	v_fma_f32 v0, -v35, v36, 1.0
	v_fmac_f32_e32 v36, v0, v36
	v_div_scale_f32 v0, vcc, v34, v148, v34
	v_mul_f32_e32 v37, v0, v36
	v_fma_f32 v38, -v35, v37, v0
	v_fmac_f32_e32 v37, v38, v36
	v_fma_f32 v0, -v35, v37, v0
	v_div_fmas_f32 v0, v0, v36, v37
	v_div_fixup_f32 v0, v0, v148, v34
	v_readlane_b32 s3, v254, 60
	v_pk_fma_f32 v[8:9], v[68:69], v[0:1], v[8:9] op_sel_hi:[1,0,1]
	v_pk_fma_f32 v[6:7], v[66:67], v[0:1], v[6:7] op_sel_hi:[1,0,1]
	v_pk_fma_f32 v[20:21], v[72:73], v[0:1], v[20:21] op_sel_hi:[1,0,1]
	v_pk_fma_f32 v[18:19], v[70:71], v[0:1], v[18:19] op_sel_hi:[1,0,1]
	v_pk_fma_f32 v[24:25], v[84:85], v[0:1], v[24:25] op_sel_hi:[1,0,1]
	v_pk_fma_f32 v[22:23], v[82:83], v[0:1], v[22:23] op_sel_hi:[1,0,1]
	v_pk_fma_f32 v[32:33], v[88:89], v[0:1], v[32:33] op_sel_hi:[1,0,1]
	v_pk_fma_f32 v[30:31], v[86:87], v[0:1], v[30:31] op_sel_hi:[1,0,1]
	v_or_b32_e32 v0, s3, v139
	v_lshlrev_b32_e32 v0, 12, v0
	v_lshl_add_u64 v[34:35], s[92:93], 0, v[0:1]
	v_lshl_add_u64 v[34:35], v[34:35], 0, s[28:29]
	v_lshlrev_b32_e32 v0, 1, v138
	v_lshl_add_u64 v[34:35], v[34:35], 0, v[0:1]
	s_mov_b32 s2, 0x17900000
	v_cvt_pk_bf16_f32 v2, v2, v3
	v_cvt_pk_bf16_f32 v3, v4, v5
	v_add_co_u32_e32 v4, vcc, s2, v34
	v_lshl_add_u64 v[36:37], v[34:35], 0, s[24:25]
	s_nop 0
	v_addc_co_u32_e32 v5, vcc, 0, v35, vcc
	global_store_dwordx2 v[4:5], v[2:3], off offset:2048
	v_cvt_pk_bf16_f32 v2, v10, v11
	v_cvt_pk_bf16_f32 v3, v12, v13
	global_store_dwordx2 v[36:37], v[2:3], off offset:32
	v_cvt_pk_bf16_f32 v2, v14, v15
	v_cvt_pk_bf16_f32 v3, v16, v17
	global_store_dwordx2 v[36:37], v[2:3], off offset:64
	v_cvt_pk_bf16_f32 v2, v26, v27
	v_cvt_pk_bf16_f32 v3, v28, v29
	global_store_dwordx2 v[36:37], v[2:3], off offset:96
	v_or_b32_e32 v2, s3, v141
	v_lshlrev_b32_e32 v2, 12, v2
	v_mov_b32_e32 v3, v1
	v_lshl_add_u64 v[2:3], s[92:93], 0, v[2:3]
	v_lshl_add_u64 v[2:3], v[2:3], 0, s[28:29]
	v_lshl_add_u64 v[2:3], v[2:3], 0, v[0:1]
	v_lshl_add_u64 v[4:5], v[2:3], 0, s[24:25]
	v_add_co_u32_e32 v2, vcc, s2, v2
	v_cvt_pk_bf16_f32 v6, v6, v7
	v_cvt_pk_bf16_f32 v7, v8, v9
	v_addc_co_u32_e32 v3, vcc, 0, v3, vcc
	global_store_dwordx2 v[2:3], v[6:7], off offset:2048
	v_cvt_pk_bf16_f32 v2, v18, v19
	v_cvt_pk_bf16_f32 v3, v20, v21
	global_store_dwordx2 v[4:5], v[2:3], off offset:32
	v_cvt_pk_bf16_f32 v2, v22, v23
	v_cvt_pk_bf16_f32 v3, v24, v25
	global_store_dwordx2 v[4:5], v[2:3], off offset:64
	v_cvt_pk_bf16_f32 v2, v30, v31
	v_cvt_pk_bf16_f32 v3, v32, v33
	global_store_dwordx2 v[4:5], v[2:3], off offset:96
	s_setprio 0
	s_barrier
